# v075 + attention: waves 4-7 sleep ~640 cycles after the V-image barrier of every item so SIMD partners alternate MFMA and softmax VALU phases
# baseline (speedup 1.0000x reference)
; __device__ __forceinline__ float xmax32(float v) { auto r = __builtin_amdgcn_permlane32_swap(__float_as_uint(v), __float_as_uint(v), false, false); return fmaxf(__uint_as_float(r[0]), __uint_as_float(r[1])); }
; __device__ __forceinline__ int crow16(int g, int hh) { return (g & 3) + 8 * (g >> 2) + 4 * hh; }
; __device__ __forceinline__ void attn_v2(const KA& A, const Ctx& F, int l) {
;     ...
;         const int kbase = i0 + 32 * w - 128;
;         float mx = -3.0e38f;
; #pragma unroll
;         for (int kt = 0; kt < 5; ++kt) {
;             if (kt == 0 || kt == 4 || kbase < 0) {
; #pragma unroll
;                 for (int gq = 0; gq < 16; ++gq) { const int kl = crow16(gq, hh); const int dist = q + 128 - 32 * kt - kl;
;                     const bool ok = (dist >= 0) && (dist <= 128) && (kbase + 32 * kt + kl >= 0);
;                     if (!ok) p[kt][gq] = -3.0e38f; } }
; #pragma unroll
;             for (int gq = 0; gq < 16; ++gq) mx = fmaxf(mx, p[kt][gq]);
;         }
;         mx = xmax32(mx);
.LBB0_206:
	s_sub_i32 s10, 0x7f, s19
	v_cmp_lt_i32_e32 vcc, s10, v143
	s_and_b64 vcc, s[40:41], vcc
	s_waitcnt lgkmcnt(0)
	s_barrier
	v_readfirstlane_b32 s11, v242
	s_cmpk_lt_u32 s11, 0x100
	s_cbranch_scc1 .Latt_nostag
	s_sleep 10
.Latt_nostag:
	v_cndmask_b32_e32 v80, v237, v48, vcc
	v_cmp_le_i32_e32 vcc, s10, v143
	s_and_b64 vcc, s[42:43], vcc
	s_nop 0
	v_cndmask_b32_e32 v82, v237, v49, vcc
	v_cmp_lt_i32_e32 vcc, s10, v144
	s_and_b64 vcc, s[44:45], vcc
	s_nop 0
	v_cndmask_b32_e32 v83, v237, v50, vcc
	v_cmp_lt_i32_e32 vcc, s10, v145
	s_and_b64 vcc, s[46:47], vcc
	s_nop 0
	v_cndmask_b32_e32 v51, v237, v51, vcc
	v_cmp_lt_i32_e32 vcc, s10, v146
	s_and_b64 vcc, s[48:49], vcc
	s_nop 0
	v_cndmask_b32_e32 v84, v237, v52, vcc
	v_cmp_lt_i32_e32 vcc, s10, v147
	s_and_b64 vcc, s[50:51], vcc
	s_nop 0
	v_cndmask_b32_e32 v53, v237, v53, vcc
	v_cmp_lt_i32_e32 vcc, s10, v148
	s_and_b64 vcc, s[52:53], vcc
	s_nop 0
	v_cndmask_b32_e32 v54, v237, v54, vcc
	v_cmp_lt_i32_e32 vcc, s10, v149
	s_and_b64 vcc, s[54:55], vcc
	s_nop 0
	v_cndmask_b32_e32 v55, v237, v55, vcc
	v_cmp_lt_i32_e32 vcc, s10, v150
	s_and_b64 vcc, s[56:57], vcc
	s_nop 0
	v_cndmask_b32_e32 v56, v237, v56, vcc
	v_cmp_lt_i32_e32 vcc, s10, v151
	s_and_b64 vcc, s[58:59], vcc
	s_nop 0
	v_cndmask_b32_e32 v57, v237, v57, vcc
	v_cmp_lt_i32_e32 vcc, s10, v152
	s_and_b64 vcc, s[60:61], vcc
	s_nop 0
	v_cndmask_b32_e32 v58, v237, v58, vcc
	v_cmp_lt_i32_e32 vcc, s10, v153
	s_and_b64 vcc, s[62:63], vcc
	s_nop 0
	v_cndmask_b32_e32 v59, v237, v59, vcc
	v_cmp_lt_i32_e32 vcc, s10, v154
	s_and_b64 vcc, s[64:65], vcc
	s_nop 0
	v_cndmask_b32_e32 v60, v237, v60, vcc
	v_cmp_lt_i32_e32 vcc, s10, v155
	s_and_b64 vcc, s[66:67], vcc
	s_nop 0
	v_cndmask_b32_e32 v61, v237, v61, vcc
	v_cmp_lt_i32_e32 vcc, s10, v156
	s_and_b64 vcc, s[68:69], vcc
	s_nop 0
	v_cndmask_b32_e32 v62, v237, v62, vcc
	v_cmp_lt_i32_e32 vcc, s10, v157
	s_mov_b32 s10, 0xff61b1e6
	v_max3_f32 v48, v80, s10, v82
	v_max3_f32 v48, v48, v83, v51
	v_max3_f32 v48, v48, v84, v53
	v_max3_f32 v48, v48, v54, v55
	v_max3_f32 v48, v48, v56, v57
	s_and_b64 vcc, s[70:71], vcc
	v_max3_f32 v48, v48, v58, v59
	s_not_b32 s10, s19
	v_cndmask_b32_e32 v63, v237, v63, vcc
	v_max3_f32 v48, v48, v60, v61
	v_cmp_lt_i32_e32 vcc, s10, v143
	v_max3_f32 v48, v48, v62, v63
	s_and_b64 vcc, s[72:73], vcc
	v_max3_f32 v48, v48, v32, v33
	v_cndmask_b32_e32 v128, v237, v64, vcc
	v_cmp_le_i32_e32 vcc, s10, v143
	v_max3_f32 v48, v48, v34, v35
	s_and_b64 vcc, s[74:75], vcc
	v_max3_f32 v48, v48, v36, v37
	v_cndmask_b32_e32 v127, v237, v65, vcc
	v_cmp_lt_i32_e32 vcc, s10, v144
	v_max3_f32 v48, v48, v38, v39
	s_and_b64 vcc, s[76:77], vcc
	v_max3_f32 v48, v48, v40, v41
	v_cndmask_b32_e32 v126, v237, v66, vcc
	v_cmp_lt_i32_e32 vcc, s10, v145
	v_max3_f32 v48, v48, v42, v43
	s_and_b64 vcc, s[78:79], vcc
	v_max3_f32 v48, v48, v44, v45
	v_cndmask_b32_e32 v125, v237, v67, vcc
	v_cmp_gt_i32_e32 vcc, s19, v158
	v_max3_f32 v48, v48, v46, v47
	s_and_b64 vcc, s[80:81], vcc
	v_max3_f32 v48, v48, v16, v17
	v_cndmask_b32_e32 v124, v237, v68, vcc
	v_cmp_gt_i32_e32 vcc, s19, v159
	v_max3_f32 v48, v48, v18, v19
	s_and_b64 vcc, s[26:27], vcc
	v_max3_f32 v48, v48, v20, v21
	v_cndmask_b32_e32 v49, v237, v69, vcc
	v_cmp_gt_i32_e32 vcc, s19, v160
	v_max3_f32 v48, v48, v22, v23
	s_and_b64 vcc, s[84:85], vcc
	v_max3_f32 v48, v48, v24, v25
	v_cndmask_b32_e32 v50, v237, v70, vcc
	v_cmp_gt_i32_e32 vcc, s19, v161
	v_max3_f32 v48, v48, v26, v27
	s_and_b64 vcc, s[86:87], vcc
	v_max3_f32 v48, v48, v28, v29
	v_cndmask_b32_e32 v52, v237, v71, vcc
	v_cmp_gt_i32_e32 vcc, s19, v162
	v_max3_f32 v48, v48, v30, v31
	s_and_b64 vcc, s[88:89], vcc
	v_max3_f32 v48, v48, v0, v1
	v_cndmask_b32_e32 v123, v237, v72, vcc
	v_cmp_gt_i32_e32 vcc, s19, v163
	v_max3_f32 v48, v48, v2, v3
	s_and_b64 vcc, s[90:91], vcc
	v_max3_f32 v48, v48, v4, v5
	v_cndmask_b32_e32 v122, v237, v73, vcc
	v_cmp_gt_i32_e32 vcc, s19, v164
	v_max3_f32 v48, v48, v6, v7
; __device__ __forceinline__ float xsum32(float v) { auto r = __builtin_amdgcn_permlane32_swap(__float_as_uint(v), __float_as_uint(v), false, false); return __uint_as_float(r[0]) + __uint_as_float(r[1]); }
; __device__ __forceinline__ float xmax32(float v) { auto r = __builtin_amdgcn_permlane32_swap(__float_as_uint(v), __float_as_uint(v), false, false); return fmaxf(__uint_as_float(r[0]), __uint_as_float(r[1])); }
; __device__ __forceinline__ void attn_v2(const KA& A, const Ctx& F, int l) {
;     ...
;         else { if (F.tid == 0) *slot = 256u + __hip_atomic_fetch_add(ctr, 1u, __ATOMIC_RELAXED, __HIP_MEMORY_SCOPE_AGENT);
;     ...
;         mx = xmax32(mx);
;         const float sc = 0.125f * 1.4426950408889634f;
;         float l = 0.f;
; #pragma unroll
;         for (int kt = 0; kt < 5; ++kt)
; #pragma unroll
;             for (int gq = 0; gq < 16; ++gq) { const float e = __builtin_amdgcn_exp2f((p[kt][gq] - mx) * sc); p[kt][gq] = e; l += e; }
;         l = xsum32(l);
	s_and_b64 vcc, s[92:93], vcc
	v_max3_f32 v48, v48, v8, v9
	v_cndmask_b32_e32 v121, v237, v74, vcc
	v_cmp_gt_i32_e32 vcc, s19, v165
	v_max3_f32 v48, v48, v10, v11
	s_and_b64 vcc, s[94:95], vcc
	v_max3_f32 v48, v48, v12, v13
	v_cndmask_b32_e32 v120, v237, v75, vcc
	v_cmp_gt_i32_e32 vcc, s19, v166
	v_max3_f32 v48, v48, v14, v15
	s_and_b64 vcc, s[96:97], vcc
	v_cndmask_b32_e32 v119, v237, v76, vcc
	v_cmp_gt_i32_e32 vcc, s19, v167
	v_max3_f32 v48, v48, v128, v127
	s_and_b64 vcc, s[2:3], vcc
	v_max3_f32 v48, v48, v126, v125
	v_cndmask_b32_e32 v118, v237, v77, vcc
	v_cmp_gt_i32_e32 vcc, s19, v168
	v_max3_f32 v48, v48, v124, v49
	s_and_b64 vcc, s[4:5], vcc
	v_max3_f32 v48, v48, v50, v52
	v_cndmask_b32_e32 v117, v237, v78, vcc
	v_cmp_gt_i32_e32 vcc, s19, v169
	v_max3_f32 v48, v48, v123, v122
	s_and_b64 vcc, s[6:7], vcc
	v_max3_f32 v48, v48, v121, v120
	v_cndmask_b32_e32 v116, v237, v79, vcc
	v_max3_f32 v48, v48, v119, v118
	v_max3_f32 v48, v48, v117, v116
	v_mov_b32_e32 v64, v48
	s_nop 1
	v_permlane32_swap_b32_e32 v48, v64
	v_max_f32_e32 v64, v64, v64
	v_max_f32_e32 v48, v48, v48
	v_max_f32_e32 v48, v48, v64
	v_sub_f32_e32 v64, v80, v48
	v_sub_f32_e32 v65, v82, v48
	v_sub_f32_e32 v53, v53, v48
	v_mul_f32_e32 v64, 0x3e38aa3b, v64
	v_mul_f32_e32 v65, 0x3e38aa3b, v65
	v_mul_f32_e32 v53, 0x3e38aa3b, v53
	v_exp_f32_e32 v90, v64
	v_exp_f32_e32 v92, v65
	v_sub_f32_e32 v65, v83, v48
	v_exp_f32_e32 v108, v53
	v_sub_f32_e32 v53, v54, v48
	v_mul_f32_e32 v65, 0x3e38aa3b, v65
	v_sub_f32_e32 v51, v51, v48
	v_mul_f32_e32 v53, 0x3e38aa3b, v53
	v_exp_f32_e32 v95, v65
	v_mul_f32_e32 v51, 0x3e38aa3b, v51
	v_exp_f32_e32 v110, v53
	v_sub_f32_e32 v53, v55, v48
	v_exp_f32_e32 v98, v51
	v_mul_f32_e32 v53, 0x3e38aa3b, v53
	v_add_f32_e32 v64, 0, v90
	v_exp_f32_e32 v112, v53
	v_sub_f32_e32 v53, v56, v48
	v_add_f32_e32 v64, v92, v64
	v_mul_f32_e32 v53, 0x3e38aa3b, v53
	v_add_f32_e32 v64, v95, v64
	v_exp_f32_e32 v91, v53
	v_sub_f32_e32 v53, v57, v48
	v_sub_f32_e32 v33, v33, v48
	v_add_f32_e32 v51, v98, v64
	v_sub_f32_e32 v64, v84, v48
	v_mul_f32_e32 v53, 0x3e38aa3b, v53
	v_mul_f32_e32 v33, 0x3e38aa3b, v33
	v_mul_f32_e32 v64, 0x3e38aa3b, v64
	v_exp_f32_e32 v99, v53
	v_sub_f32_e32 v53, v58, v48
	v_exp_f32_e32 v87, v33
	v_sub_f32_e32 v33, v34, v48
	v_exp_f32_e32 v102, v64
	v_mul_f32_e32 v53, 0x3e38aa3b, v53
	v_mul_f32_e32 v33, 0x3e38aa3b, v33
	v_exp_f32_e32 v103, v53
	v_sub_f32_e32 v53, v59, v48
	v_exp_f32_e32 v93, v33
	v_sub_f32_e32 v33, v35, v48
	v_mul_f32_e32 v53, 0x3e38aa3b, v53
	v_mul_f32_e32 v33, 0x3e38aa3b, v33
	v_exp_f32_e32 v105, v53
	v_sub_f32_e32 v53, v60, v48
	v_exp_f32_e32 v96, v33
	v_sub_f32_e32 v33, v36, v48
	v_add_f32_e32 v51, v102, v51
	v_mul_f32_e32 v53, 0x3e38aa3b, v53
	v_mul_f32_e32 v33, 0x3e38aa3b, v33
	v_add_f32_e32 v51, v108, v51
	v_exp_f32_e32 v107, v53
	v_sub_f32_e32 v53, v61, v48
	v_exp_f32_e32 v100, v33
	v_sub_f32_e32 v33, v37, v48
	v_add_f32_e32 v51, v110, v51
	v_mul_f32_e32 v53, 0x3e38aa3b, v53
	v_mul_f32_e32 v33, 0x3e38aa3b, v33
	v_add_f32_e32 v51, v112, v51
	v_exp_f32_e32 v113, v53
	v_sub_f32_e32 v53, v62, v48
	v_exp_f32_e32 v106, v33
	v_sub_f32_e32 v33, v38, v48
	v_add_f32_e32 v51, v91, v51
	v_mul_f32_e32 v53, 0x3e38aa3b, v53
	v_mul_f32_e32 v33, 0x3e38aa3b, v33
	v_add_f32_e32 v51, v99, v51
	v_exp_f32_e32 v114, v53
	v_sub_f32_e32 v53, v63, v48
	v_exp_f32_e32 v109, v33
	v_sub_f32_e32 v33, v39, v48
	v_add_f32_e32 v51, v103, v51
	v_mul_f32_e32 v53, 0x3e38aa3b, v53
	v_sub_f32_e32 v32, v32, v48
	v_mul_f32_e32 v33, 0x3e38aa3b, v33
	v_add_f32_e32 v51, v105, v51
	v_exp_f32_e32 v115, v53
	v_mul_f32_e32 v32, 0x3e38aa3b, v32
	v_exp_f32_e32 v111, v33
	v_sub_f32_e32 v33, v40, v48
	v_add_f32_e32 v51, v107, v51
	v_exp_f32_e32 v82, v32
	v_mul_f32_e32 v33, 0x3e38aa3b, v33
	v_add_f32_e32 v51, v113, v51
	v_exp_f32_e32 v73, v33
	s_mov_b64 exec, s[8:9]
	s_cbranch_execz .Latt_pf_skip
	v_mov_b32_e32 v178, 1
	s_nop 0
	global_atomic_add v178, v81, v178, s[16:17] sc0
